# GEMM K-loops: all s_setprio removed plus redundant post-barrier lgkmcnt(0)
# speedup vs baseline: 1.0070x; 1.0020x over previous
.LBB0_176:
	ds_read_b128 v[58:61], v219
	ds_read_b128 v[62:65], v219 offset:1024
	ds_read_b128 v[78:81], v219 offset:2048
	ds_read_b128 v[82:85], v219 offset:3072
	ds_read_b128 v[102:105], v220
	ds_read_b128 v[106:109], v220 offset:1024
	ds_read_b128 v[122:125], v220 offset:2048
	ds_read_b128 v[126:129], v220 offset:3072
	s_add_u32 s42, s40, 0xfff80080
	s_addc_u32 s43, s41, -1
	s_cmp_eq_u32 s52, 28
	s_cselect_b32 s45, s2, s43
	s_cselect_b32 s44, s29, s42
	s_cselect_b32 s43, s27, s47
	s_cselect_b32 s42, s39, s46
	v_lshl_add_u64 v[212:213], s[40:41], 0, v[206:207]
	s_add_i32 m0, s49, 0xc000
	ds_read_b128 v[146:149], v221
	ds_read_b128 v[150:153], v221 offset:1024
	ds_read_b128 v[170:173], v221 offset:2048
	ds_read_b128 v[174:177], v221 offset:3072
	ds_read_b128 v[178:181], v221 offset:4096
	ds_read_b128 v[182:185], v221 offset:5120
	ds_read_b128 v[186:189], v221 offset:6144
	ds_read_b128 v[190:193], v221 offset:7168
	global_load_lds_dwordx4 v[212:213], off
	v_lshl_add_u64 v[212:213], s[40:41], 0, v[208:209]
	s_add_i32 m0, s49, 0xe000
	s_nop 0
	global_load_lds_dwordx4 v[212:213], off
	s_waitcnt vmcnt(8)
	s_waitcnt lgkmcnt(0)
	s_barrier
	v_mfma_f32_16x16x32_bf16 v[166:169], v[58:61], v[146:149], v[166:169]
	v_mfma_f32_16x16x32_bf16 v[162:165], v[78:81], v[146:149], v[162:165]
	v_mfma_f32_16x16x32_bf16 v[142:145], v[58:61], v[170:173], v[142:145]
	v_mfma_f32_16x16x32_bf16 v[138:141], v[78:81], v[170:173], v[138:141]
	v_mfma_f32_16x16x32_bf16 v[118:121], v[58:61], v[178:181], v[118:121]
	v_mfma_f32_16x16x32_bf16 v[114:117], v[78:81], v[178:181], v[114:117]
	v_mfma_f32_16x16x32_bf16 v[94:97], v[58:61], v[186:189], v[94:97]
	v_mfma_f32_16x16x32_bf16 v[90:93], v[78:81], v[186:189], v[90:93]
	v_mfma_f32_16x16x32_bf16 v[166:169], v[62:65], v[150:153], v[166:169]
	v_mfma_f32_16x16x32_bf16 v[162:165], v[82:85], v[150:153], v[162:165]
	v_mfma_f32_16x16x32_bf16 v[142:145], v[62:65], v[174:177], v[142:145]
	v_mfma_f32_16x16x32_bf16 v[138:141], v[82:85], v[174:177], v[138:141]
	v_mfma_f32_16x16x32_bf16 v[118:121], v[62:65], v[182:185], v[118:121]
	v_mfma_f32_16x16x32_bf16 v[114:117], v[82:85], v[182:185], v[114:117]
	v_mfma_f32_16x16x32_bf16 v[94:97], v[62:65], v[190:193], v[94:97]
	v_mfma_f32_16x16x32_bf16 v[90:93], v[82:85], v[190:193], v[90:93]
	v_mfma_f32_16x16x32_bf16 v[158:161], v[102:105], v[146:149], v[158:161]
	v_mfma_f32_16x16x32_bf16 v[134:137], v[102:105], v[170:173], v[134:137]
	v_mfma_f32_16x16x32_bf16 v[130:133], v[122:125], v[170:173], v[130:133]
	v_mfma_f32_16x16x32_bf16 v[110:113], v[102:105], v[178:181], v[110:113]
	v_mfma_f32_16x16x32_bf16 v[98:101], v[122:125], v[178:181], v[98:101]
	v_mfma_f32_16x16x32_bf16 v[86:89], v[102:105], v[186:189], v[86:89]
	v_mfma_f32_16x16x32_bf16 v[74:77], v[122:125], v[186:189], v[74:77]
	v_mfma_f32_16x16x32_bf16 v[158:161], v[106:109], v[150:153], v[158:161]
	v_mfma_f32_16x16x32_bf16 v[146:149], v[122:125], v[146:149], v[154:157]
	v_mfma_f32_16x16x32_bf16 v[134:137], v[106:109], v[174:177], v[134:137]
	v_mfma_f32_16x16x32_bf16 v[130:133], v[126:129], v[174:177], v[130:133]
	v_mfma_f32_16x16x32_bf16 v[110:113], v[106:109], v[182:185], v[110:113]
	v_mfma_f32_16x16x32_bf16 v[98:101], v[126:129], v[182:185], v[98:101]
	v_mfma_f32_16x16x32_bf16 v[86:89], v[106:109], v[190:193], v[86:89]
	v_mfma_f32_16x16x32_bf16 v[74:77], v[126:129], v[190:193], v[74:77]
	v_mfma_f32_16x16x32_bf16 v[146:149], v[126:129], v[150:153], v[146:149]
	s_barrier
	s_add_i32 s53, s86, s48
	v_lshl_add_u64 v[212:213], s[42:43], 0, v[198:199]
	s_mov_b32 m0, s53
	ds_read_b128 v[150:153], v221 offset:16384
	ds_read_b128 v[154:157], v221 offset:17408
	ds_read_b128 v[170:173], v221 offset:18432
	ds_read_b128 v[174:177], v221 offset:19456
	ds_read_b128 v[178:181], v221 offset:20480
	ds_read_b128 v[182:185], v221 offset:21504
	ds_read_b128 v[186:189], v221 offset:22528
	ds_read_b128 v[190:193], v221 offset:23552
	global_load_lds_dwordx4 v[212:213], off
	s_add_i32 m0, s53, 0x2000
	s_add_u32 s54, s42, 0x80000
	v_lshl_add_u64 v[214:215], s[42:43], 0, v[202:203]
	s_addc_u32 s55, s43, 0
	s_add_i32 s53, s87, s48
	global_load_lds_dwordx4 v[214:215], off
	v_lshl_add_u64 v[216:217], s[54:55], 0, v[198:199]
	s_mov_b32 m0, s53
	v_lshl_add_u64 v[222:223], s[44:45], 0, v[200:201]
	global_load_lds_dwordx4 v[216:217], off
	v_lshl_add_u64 v[216:217], s[54:55], 0, v[202:203]
	s_add_i32 m0, s53, 0x2000
	s_nop 0
	global_load_lds_dwordx4 v[216:217], off
	v_lshl_add_u64 v[216:217], s[44:45], 0, v[196:197]
	s_mov_b32 m0, s49
	s_nop 0
	global_load_lds_dwordx4 v[216:217], off
	s_mov_b32 m0, s50
	s_nop 0
	global_load_lds_dwordx4 v[222:223], off
	s_waitcnt vmcnt(8)
	s_waitcnt lgkmcnt(0)
	s_barrier
	v_mfma_f32_16x16x32_bf16 v[70:73], v[58:61], v[150:153], v[70:73]
	v_mfma_f32_16x16x32_bf16 v[66:69], v[78:81], v[150:153], v[66:69]
	v_mfma_f32_16x16x32_bf16 v[46:49], v[58:61], v[170:173], v[46:49]
	v_mfma_f32_16x16x32_bf16 v[42:45], v[78:81], v[170:173], v[42:45]
	v_mfma_f32_16x16x32_bf16 v[30:33], v[58:61], v[178:181], v[30:33]
	v_mfma_f32_16x16x32_bf16 v[26:29], v[78:81], v[178:181], v[26:29]
	v_mfma_f32_16x16x32_bf16 v[14:17], v[58:61], v[186:189], v[14:17]
	v_mfma_f32_16x16x32_bf16 v[10:13], v[78:81], v[186:189], v[10:13]
	v_mfma_f32_16x16x32_bf16 v[70:73], v[62:65], v[154:157], v[70:73]
	v_mfma_f32_16x16x32_bf16 v[66:69], v[82:85], v[154:157], v[66:69]
	v_mfma_f32_16x16x32_bf16 v[46:49], v[62:65], v[174:177], v[46:49]
	v_mfma_f32_16x16x32_bf16 v[42:45], v[82:85], v[174:177], v[42:45]
	v_mfma_f32_16x16x32_bf16 v[30:33], v[62:65], v[182:185], v[30:33]
	v_mfma_f32_16x16x32_bf16 v[26:29], v[82:85], v[182:185], v[26:29]
	v_mfma_f32_16x16x32_bf16 v[14:17], v[62:65], v[190:193], v[14:17]
	v_mfma_f32_16x16x32_bf16 v[10:13], v[82:85], v[190:193], v[10:13]
	v_mfma_f32_16x16x32_bf16 v[54:57], v[102:105], v[150:153], v[54:57]
	v_mfma_f32_16x16x32_bf16 v[50:53], v[122:125], v[150:153], v[50:53]
	v_mfma_f32_16x16x32_bf16 v[38:41], v[102:105], v[170:173], v[38:41]
	v_mfma_f32_16x16x32_bf16 v[34:37], v[122:125], v[170:173], v[34:37]
	v_mfma_f32_16x16x32_bf16 v[22:25], v[102:105], v[178:181], v[22:25]
	v_mfma_f32_16x16x32_bf16 v[18:21], v[122:125], v[178:181], v[18:21]
	v_mfma_f32_16x16x32_bf16 v[6:9], v[102:105], v[186:189], v[6:9]
	v_mfma_f32_16x16x32_bf16 v[2:5], v[122:125], v[186:189], v[2:5]
	v_mfma_f32_16x16x32_bf16 v[54:57], v[106:109], v[154:157], v[54:57]
	v_mfma_f32_16x16x32_bf16 v[50:53], v[126:129], v[154:157], v[50:53]
	v_mfma_f32_16x16x32_bf16 v[38:41], v[106:109], v[174:177], v[38:41]
	v_mfma_f32_16x16x32_bf16 v[34:37], v[126:129], v[174:177], v[34:37]
	v_mfma_f32_16x16x32_bf16 v[22:25], v[106:109], v[182:185], v[22:25]
	v_mfma_f32_16x16x32_bf16 v[18:21], v[126:129], v[182:185], v[18:21]
	v_mfma_f32_16x16x32_bf16 v[6:9], v[106:109], v[190:193], v[6:9]
	v_mfma_f32_16x16x32_bf16 v[2:5], v[126:129], v[190:193], v[2:5]
	s_barrier
	s_add_i32 s53, 0, 0x18000
	s_add_i32 s54, 0, 0x1c000
	v_add_u32_e32 v82, s53, v218
	v_add_u32_e32 v126, s54, v218
	ds_read_b128 v[58:61], v82
	ds_read_b128 v[62:65], v82 offset:1024
	ds_read_b128 v[78:81], v82 offset:2048
	ds_read_b128 v[82:85], v82 offset:3072
	ds_read_b128 v[102:105], v126
	ds_read_b128 v[106:109], v126 offset:1024
	ds_read_b128 v[122:125], v126 offset:2048
	ds_read_b128 v[126:129], v126 offset:3072
	s_add_u32 s44, s44, 0x80000
	s_addc_u32 s45, s45, 0
	s_mov_b32 m0, s51
	v_lshl_add_u64 v[224:225], s[44:45], 0, v[196:197]
	ds_read_b128 v[150:153], v221 offset:32768
	ds_read_b128 v[154:157], v221 offset:33792
	ds_read_b128 v[170:173], v221 offset:34816
	ds_read_b128 v[174:177], v221 offset:35840
	ds_read_b128 v[178:181], v221 offset:36864
	ds_read_b128 v[182:185], v221 offset:37888
	ds_read_b128 v[186:189], v221 offset:38912
	ds_read_b128 v[190:193], v221 offset:39936
	global_load_lds_dwordx4 v[224:225], off
	v_lshl_add_u64 v[224:225], s[44:45], 0, v[200:201]
	s_mov_b32 m0, s72
	s_nop 0
	global_load_lds_dwordx4 v[224:225], off
	s_waitcnt vmcnt(8)
	s_waitcnt lgkmcnt(0)
	s_barrier
	v_mfma_f32_16x16x32_bf16 v[166:169], v[58:61], v[150:153], v[166:169]
	v_mfma_f32_16x16x32_bf16 v[162:165], v[78:81], v[150:153], v[162:165]
	v_mfma_f32_16x16x32_bf16 v[142:145], v[58:61], v[170:173], v[142:145]
	v_mfma_f32_16x16x32_bf16 v[138:141], v[78:81], v[170:173], v[138:141]
	v_mfma_f32_16x16x32_bf16 v[118:121], v[58:61], v[178:181], v[118:121]
	v_mfma_f32_16x16x32_bf16 v[114:117], v[78:81], v[178:181], v[114:117]
	v_mfma_f32_16x16x32_bf16 v[94:97], v[58:61], v[186:189], v[94:97]
	v_mfma_f32_16x16x32_bf16 v[90:93], v[78:81], v[186:189], v[90:93]
	v_mfma_f32_16x16x32_bf16 v[166:169], v[62:65], v[154:157], v[166:169]
	v_mfma_f32_16x16x32_bf16 v[162:165], v[82:85], v[154:157], v[162:165]
	v_mfma_f32_16x16x32_bf16 v[142:145], v[62:65], v[174:177], v[142:145]
	v_mfma_f32_16x16x32_bf16 v[138:141], v[82:85], v[174:177], v[138:141]
	v_mfma_f32_16x16x32_bf16 v[118:121], v[62:65], v[182:185], v[118:121]
	v_mfma_f32_16x16x32_bf16 v[114:117], v[82:85], v[182:185], v[114:117]
	v_mfma_f32_16x16x32_bf16 v[94:97], v[62:65], v[190:193], v[94:97]
	v_mfma_f32_16x16x32_bf16 v[90:93], v[82:85], v[190:193], v[90:93]
	v_mfma_f32_16x16x32_bf16 v[158:161], v[102:105], v[150:153], v[158:161]
	v_mfma_f32_16x16x32_bf16 v[146:149], v[122:125], v[150:153], v[146:149]
	v_mfma_f32_16x16x32_bf16 v[134:137], v[102:105], v[170:173], v[134:137]
	v_mfma_f32_16x16x32_bf16 v[130:133], v[122:125], v[170:173], v[130:133]
	v_mfma_f32_16x16x32_bf16 v[110:113], v[102:105], v[178:181], v[110:113]
	v_mfma_f32_16x16x32_bf16 v[98:101], v[122:125], v[178:181], v[98:101]
	v_mfma_f32_16x16x32_bf16 v[86:89], v[102:105], v[186:189], v[86:89]
	v_mfma_f32_16x16x32_bf16 v[74:77], v[122:125], v[186:189], v[74:77]
	v_mfma_f32_16x16x32_bf16 v[158:161], v[106:109], v[154:157], v[158:161]
	v_mfma_f32_16x16x32_bf16 v[154:157], v[126:129], v[154:157], v[146:149]
	v_mfma_f32_16x16x32_bf16 v[134:137], v[106:109], v[174:177], v[134:137]
	v_mfma_f32_16x16x32_bf16 v[130:133], v[126:129], v[174:177], v[130:133]
	v_mfma_f32_16x16x32_bf16 v[110:113], v[106:109], v[182:185], v[110:113]
	v_mfma_f32_16x16x32_bf16 v[98:101], v[126:129], v[182:185], v[98:101]
	v_mfma_f32_16x16x32_bf16 v[86:89], v[106:109], v[190:193], v[86:89]
	v_mfma_f32_16x16x32_bf16 v[74:77], v[126:129], v[190:193], v[74:77]
	s_barrier
	s_add_i32 s44, s53, s48
	v_lshl_add_u64 v[212:213], v[212:213], 0, s[12:13]
	s_mov_b32 m0, s44
	ds_read_b128 v[146:149], v221 offset:49152
	ds_read_b128 v[150:153], v221 offset:50176
	ds_read_b128 v[170:173], v221 offset:51200
	ds_read_b128 v[174:177], v221 offset:52224
	ds_read_b128 v[178:181], v221 offset:53248
	ds_read_b128 v[182:185], v221 offset:54272
	ds_read_b128 v[186:189], v221 offset:55296
	ds_read_b128 v[190:193], v221 offset:56320
	global_load_lds_dwordx4 v[212:213], off
	s_add_i32 m0, s44, 0x2000
	s_add_u32 s42, s42, 0x80080
	v_lshl_add_u64 v[212:213], v[214:215], 0, s[12:13]
	s_addc_u32 s43, s43, 0
	s_add_i32 s44, s54, s48
	global_load_lds_dwordx4 v[212:213], off
	v_lshl_add_u64 v[212:213], s[42:43], 0, v[198:199]
	s_mov_b32 m0, s44
	s_nop 0
	global_load_lds_dwordx4 v[212:213], off
	v_lshl_add_u64 v[212:213], s[42:43], 0, v[202:203]
	s_add_i32 m0, s44, 0x2000
	s_nop 0
	global_load_lds_dwordx4 v[212:213], off
	v_lshl_add_u64 v[212:213], v[216:217], 0, s[12:13]
	s_mov_b32 m0, s79
	s_nop 0
	global_load_lds_dwordx4 v[212:213], off
	v_lshl_add_u64 v[212:213], v[222:223], 0, s[12:13]
	s_mov_b32 m0, s80
	s_nop 0
	global_load_lds_dwordx4 v[212:213], off
	s_waitcnt vmcnt(8)
	s_waitcnt lgkmcnt(0)
	s_barrier
	v_mfma_f32_16x16x32_bf16 v[70:73], v[58:61], v[146:149], v[70:73]
	v_mfma_f32_16x16x32_bf16 v[66:69], v[78:81], v[146:149], v[66:69]
	v_mfma_f32_16x16x32_bf16 v[46:49], v[58:61], v[170:173], v[46:49]
	v_mfma_f32_16x16x32_bf16 v[42:45], v[78:81], v[170:173], v[42:45]
	v_mfma_f32_16x16x32_bf16 v[30:33], v[58:61], v[178:181], v[30:33]
	v_mfma_f32_16x16x32_bf16 v[26:29], v[78:81], v[178:181], v[26:29]
	v_mfma_f32_16x16x32_bf16 v[14:17], v[58:61], v[186:189], v[14:17]
	v_mfma_f32_16x16x32_bf16 v[10:13], v[78:81], v[186:189], v[10:13]
	v_mfma_f32_16x16x32_bf16 v[70:73], v[62:65], v[150:153], v[70:73]
	v_mfma_f32_16x16x32_bf16 v[66:69], v[82:85], v[150:153], v[66:69]
	v_mfma_f32_16x16x32_bf16 v[46:49], v[62:65], v[174:177], v[46:49]
	v_mfma_f32_16x16x32_bf16 v[42:45], v[82:85], v[174:177], v[42:45]
	v_mfma_f32_16x16x32_bf16 v[30:33], v[62:65], v[182:185], v[30:33]
	v_mfma_f32_16x16x32_bf16 v[26:29], v[82:85], v[182:185], v[26:29]
	v_mfma_f32_16x16x32_bf16 v[14:17], v[62:65], v[190:193], v[14:17]
	v_mfma_f32_16x16x32_bf16 v[10:13], v[82:85], v[190:193], v[10:13]
	v_mfma_f32_16x16x32_bf16 v[54:57], v[102:105], v[146:149], v[54:57]
	v_mfma_f32_16x16x32_bf16 v[50:53], v[122:125], v[146:149], v[50:53]
	v_mfma_f32_16x16x32_bf16 v[38:41], v[102:105], v[170:173], v[38:41]
	v_mfma_f32_16x16x32_bf16 v[34:37], v[122:125], v[170:173], v[34:37]
	v_mfma_f32_16x16x32_bf16 v[22:25], v[102:105], v[178:181], v[22:25]
	v_mfma_f32_16x16x32_bf16 v[18:21], v[122:125], v[178:181], v[18:21]
	v_mfma_f32_16x16x32_bf16 v[6:9], v[102:105], v[186:189], v[6:9]
	v_mfma_f32_16x16x32_bf16 v[2:5], v[122:125], v[186:189], v[2:5]
	v_mfma_f32_16x16x32_bf16 v[54:57], v[106:109], v[150:153], v[54:57]
	v_mfma_f32_16x16x32_bf16 v[50:53], v[126:129], v[150:153], v[50:53]
	v_mfma_f32_16x16x32_bf16 v[38:41], v[106:109], v[174:177], v[38:41]
	v_mfma_f32_16x16x32_bf16 v[34:37], v[126:129], v[174:177], v[34:37]
	v_mfma_f32_16x16x32_bf16 v[22:25], v[106:109], v[182:185], v[22:25]
	v_mfma_f32_16x16x32_bf16 v[18:21], v[126:129], v[182:185], v[18:21]
	v_mfma_f32_16x16x32_bf16 v[6:9], v[106:109], v[190:193], v[6:9]
	v_mfma_f32_16x16x32_bf16 v[2:5], v[126:129], v[190:193], v[2:5]
	s_barrier
	s_add_i32 s52, s52, 2
	s_add_u32 s46, s46, 0x100
	s_addc_u32 s47, s47, 0
	s_add_u32 s40, s40, 0x100
	s_addc_u32 s41, s41, 0
	s_cmp_gt_u32 s52, 29
	s_cbranch_scc0 .LBB0_176
	s_and_b64 vcc, exec, s[24:25]
	s_cbranch_vccz .LBB0_179
	s_barrier

.LBB0_651:
	ds_read_b128 v[140:143], v197
	ds_read_b128 v[144:147], v197 offset:1024
	ds_read_b128 v[148:151], v197 offset:2048
	ds_read_b128 v[152:155], v197 offset:3072
	ds_read_b128 v[156:159], v198
	ds_read_b128 v[160:163], v198 offset:1024
	ds_read_b128 v[164:167], v198 offset:2048
	ds_read_b128 v[168:171], v198 offset:3072
	s_add_u32 s28, s26, 0xfff80080
	s_addc_u32 s29, s27, -1
	s_cmp_eq_u32 s46, 28
	s_cselect_b32 s31, s15, s29
	s_cselect_b32 s30, s23, s28
	s_cselect_b32 s29, s13, s45
	s_cselect_b32 s28, s43, s44
	v_lshl_add_u64 v[192:193], s[26:27], 0, v[134:135]
	s_add_i32 m0, s25, 0xc000
	ds_read_b128 v[172:175], v199
	ds_read_b128 v[176:179], v199 offset:1024
	ds_read_b128 v[180:183], v199 offset:2048
	ds_read_b128 v[184:187], v199 offset:3072
	ds_read_b128 v[188:191], v199 offset:4096
	ds_read_b128 v[202:205], v199 offset:5120
	ds_read_b128 v[206:209], v199 offset:6144
	ds_read_b128 v[210:213], v199 offset:7168
	global_load_lds_dwordx4 v[192:193], off
	v_lshl_add_u64 v[192:193], s[26:27], 0, v[136:137]
	s_add_i32 m0, s25, 0xe000
	s_nop 0
	global_load_lds_dwordx4 v[192:193], off
	s_waitcnt vmcnt(8)
	s_waitcnt lgkmcnt(0)
	s_barrier
	v_mfma_f32_16x16x32_bf16 v[126:129], v[140:143], v[172:175], v[126:129]
	v_mfma_f32_16x16x32_bf16 v[122:125], v[148:151], v[172:175], v[122:125]
	v_mfma_f32_16x16x32_bf16 v[110:113], v[140:143], v[180:183], v[110:113]
	v_mfma_f32_16x16x32_bf16 v[106:109], v[148:151], v[180:183], v[106:109]
	v_mfma_f32_16x16x32_bf16 v[94:97], v[140:143], v[188:191], v[94:97]
	v_mfma_f32_16x16x32_bf16 v[90:93], v[148:151], v[188:191], v[90:93]
	v_mfma_f32_16x16x32_bf16 v[78:81], v[140:143], v[206:209], v[78:81]
	v_mfma_f32_16x16x32_bf16 v[74:77], v[148:151], v[206:209], v[74:77]
	v_mfma_f32_16x16x32_bf16 v[126:129], v[144:147], v[176:179], v[126:129]
	v_mfma_f32_16x16x32_bf16 v[122:125], v[152:155], v[176:179], v[122:125]
	v_mfma_f32_16x16x32_bf16 v[110:113], v[144:147], v[184:187], v[110:113]
	v_mfma_f32_16x16x32_bf16 v[106:109], v[152:155], v[184:187], v[106:109]
	v_mfma_f32_16x16x32_bf16 v[94:97], v[144:147], v[202:205], v[94:97]
	v_mfma_f32_16x16x32_bf16 v[90:93], v[152:155], v[202:205], v[90:93]
	v_mfma_f32_16x16x32_bf16 v[78:81], v[144:147], v[210:213], v[78:81]
	v_mfma_f32_16x16x32_bf16 v[74:77], v[152:155], v[210:213], v[74:77]
	v_mfma_f32_16x16x32_bf16 v[118:121], v[156:159], v[172:175], v[118:121]
	v_mfma_f32_16x16x32_bf16 v[114:117], v[164:167], v[172:175], v[114:117]
	v_mfma_f32_16x16x32_bf16 v[102:105], v[156:159], v[180:183], v[102:105]
	v_mfma_f32_16x16x32_bf16 v[98:101], v[164:167], v[180:183], v[98:101]
	v_mfma_f32_16x16x32_bf16 v[86:89], v[156:159], v[188:191], v[86:89]
	v_mfma_f32_16x16x32_bf16 v[82:85], v[164:167], v[188:191], v[82:85]
	v_mfma_f32_16x16x32_bf16 v[70:73], v[156:159], v[206:209], v[70:73]
	v_mfma_f32_16x16x32_bf16 v[66:69], v[164:167], v[206:209], v[66:69]
	v_mfma_f32_16x16x32_bf16 v[118:121], v[160:163], v[176:179], v[118:121]
	v_mfma_f32_16x16x32_bf16 v[114:117], v[168:171], v[176:179], v[114:117]
	v_mfma_f32_16x16x32_bf16 v[102:105], v[160:163], v[184:187], v[102:105]
	v_mfma_f32_16x16x32_bf16 v[98:101], v[168:171], v[184:187], v[98:101]
	v_mfma_f32_16x16x32_bf16 v[86:89], v[160:163], v[202:205], v[86:89]
	v_mfma_f32_16x16x32_bf16 v[82:85], v[168:171], v[202:205], v[82:85]
	v_mfma_f32_16x16x32_bf16 v[70:73], v[160:163], v[210:213], v[70:73]
	v_mfma_f32_16x16x32_bf16 v[66:69], v[168:171], v[210:213], v[66:69]
	s_barrier
	s_add_i32 s47, s2, s3
	v_lshl_add_u64 v[192:193], s[28:29], 0, v[130:131]
	s_mov_b32 m0, s47
	ds_read_b128 v[172:175], v199 offset:16384
	ds_read_b128 v[176:179], v199 offset:17408
	ds_read_b128 v[180:183], v199 offset:18432
	ds_read_b128 v[184:187], v199 offset:19456
	ds_read_b128 v[188:191], v199 offset:20480
	ds_read_b128 v[202:205], v199 offset:21504
	ds_read_b128 v[206:209], v199 offset:22528
	ds_read_b128 v[210:213], v199 offset:23552
	global_load_lds_dwordx4 v[192:193], off
	s_add_i32 m0, s47, 0x2000
	s_add_u32 s48, s28, 0x80000
	v_lshl_add_u64 v[214:215], s[28:29], 0, v[132:133]
	s_addc_u32 s49, s29, 0
	s_add_i32 s47, s42, s3
	global_load_lds_dwordx4 v[214:215], off
	v_lshl_add_u64 v[216:217], s[48:49], 0, v[130:131]
	s_mov_b32 m0, s47
	v_lshl_add_u64 v[218:219], s[30:31], 0, v[132:133]
	global_load_lds_dwordx4 v[216:217], off
	v_lshl_add_u64 v[216:217], s[48:49], 0, v[132:133]
	s_add_i32 m0, s47, 0x2000
	s_nop 0
	global_load_lds_dwordx4 v[216:217], off
	v_lshl_add_u64 v[216:217], s[30:31], 0, v[130:131]
	s_mov_b32 m0, s25
	s_nop 0
	global_load_lds_dwordx4 v[216:217], off
	s_mov_b32 m0, s34
	s_nop 0
	global_load_lds_dwordx4 v[218:219], off
	s_waitcnt vmcnt(8)
	s_waitcnt lgkmcnt(0)
	s_barrier
	v_mfma_f32_16x16x32_bf16 v[62:65], v[140:143], v[172:175], v[62:65]
	v_mfma_f32_16x16x32_bf16 v[58:61], v[148:151], v[172:175], v[58:61]
	v_mfma_f32_16x16x32_bf16 v[46:49], v[140:143], v[180:183], v[46:49]
	v_mfma_f32_16x16x32_bf16 v[42:45], v[148:151], v[180:183], v[42:45]
	v_mfma_f32_16x16x32_bf16 v[30:33], v[140:143], v[188:191], v[30:33]
	v_mfma_f32_16x16x32_bf16 v[26:29], v[148:151], v[188:191], v[26:29]
	v_mfma_f32_16x16x32_bf16 v[14:17], v[140:143], v[206:209], v[14:17]
	v_mfma_f32_16x16x32_bf16 v[10:13], v[148:151], v[206:209], v[10:13]
	v_mfma_f32_16x16x32_bf16 v[62:65], v[144:147], v[176:179], v[62:65]
	v_mfma_f32_16x16x32_bf16 v[58:61], v[152:155], v[176:179], v[58:61]
	v_mfma_f32_16x16x32_bf16 v[46:49], v[144:147], v[184:187], v[46:49]
	v_mfma_f32_16x16x32_bf16 v[42:45], v[152:155], v[184:187], v[42:45]
	v_mfma_f32_16x16x32_bf16 v[30:33], v[144:147], v[202:205], v[30:33]
	v_mfma_f32_16x16x32_bf16 v[26:29], v[152:155], v[202:205], v[26:29]
	v_mfma_f32_16x16x32_bf16 v[14:17], v[144:147], v[210:213], v[14:17]
	v_mfma_f32_16x16x32_bf16 v[10:13], v[152:155], v[210:213], v[10:13]
	v_mfma_f32_16x16x32_bf16 v[54:57], v[156:159], v[172:175], v[54:57]
	v_mfma_f32_16x16x32_bf16 v[50:53], v[164:167], v[172:175], v[50:53]
	v_mfma_f32_16x16x32_bf16 v[38:41], v[156:159], v[180:183], v[38:41]
	v_mfma_f32_16x16x32_bf16 v[34:37], v[164:167], v[180:183], v[34:37]
	v_mfma_f32_16x16x32_bf16 v[22:25], v[156:159], v[188:191], v[22:25]
	v_mfma_f32_16x16x32_bf16 v[18:21], v[164:167], v[188:191], v[18:21]
	v_mfma_f32_16x16x32_bf16 v[6:9], v[156:159], v[206:209], v[6:9]
	v_mfma_f32_16x16x32_bf16 v[2:5], v[164:167], v[206:209], v[2:5]
	v_mfma_f32_16x16x32_bf16 v[54:57], v[160:163], v[176:179], v[54:57]
	v_mfma_f32_16x16x32_bf16 v[50:53], v[168:171], v[176:179], v[50:53]
	v_mfma_f32_16x16x32_bf16 v[38:41], v[160:163], v[184:187], v[38:41]
	v_mfma_f32_16x16x32_bf16 v[34:37], v[168:171], v[184:187], v[34:37]
	v_mfma_f32_16x16x32_bf16 v[22:25], v[160:163], v[202:205], v[22:25]
	v_mfma_f32_16x16x32_bf16 v[18:21], v[168:171], v[202:205], v[18:21]
	v_mfma_f32_16x16x32_bf16 v[6:9], v[160:163], v[210:213], v[6:9]
	v_mfma_f32_16x16x32_bf16 v[2:5], v[168:171], v[210:213], v[2:5]
	s_barrier
	s_add_i32 s47, 0, 0x18000
	s_add_i32 s48, 0, 0x1c000
	v_add_u32_e32 v152, s47, v195
	v_add_u32_e32 v168, s48, v195
	ds_read_b128 v[140:143], v152
	ds_read_b128 v[144:147], v152 offset:1024
	ds_read_b128 v[148:151], v152 offset:2048
	ds_read_b128 v[152:155], v152 offset:3072
	ds_read_b128 v[156:159], v168
	ds_read_b128 v[160:163], v168 offset:1024
	ds_read_b128 v[164:167], v168 offset:2048
	ds_read_b128 v[168:171], v168 offset:3072
	s_add_u32 s30, s30, 0x80000
	s_addc_u32 s31, s31, 0
	s_mov_b32 m0, s35
	v_lshl_add_u64 v[220:221], s[30:31], 0, v[130:131]
	ds_read_b128 v[172:175], v199 offset:32768
	ds_read_b128 v[176:179], v199 offset:33792
	ds_read_b128 v[180:183], v199 offset:34816
	ds_read_b128 v[184:187], v199 offset:35840
	ds_read_b128 v[188:191], v199 offset:36864
	ds_read_b128 v[202:205], v199 offset:37888
	ds_read_b128 v[206:209], v199 offset:38912
	ds_read_b128 v[210:213], v199 offset:39936
	global_load_lds_dwordx4 v[220:221], off
	v_lshl_add_u64 v[220:221], s[30:31], 0, v[132:133]
	s_mov_b32 m0, s36
	s_nop 0
	global_load_lds_dwordx4 v[220:221], off
	s_waitcnt vmcnt(8)
	s_waitcnt lgkmcnt(0)
	s_barrier
	v_mfma_f32_16x16x32_bf16 v[126:129], v[140:143], v[172:175], v[126:129]
	v_mfma_f32_16x16x32_bf16 v[122:125], v[148:151], v[172:175], v[122:125]
	v_mfma_f32_16x16x32_bf16 v[110:113], v[140:143], v[180:183], v[110:113]
	v_mfma_f32_16x16x32_bf16 v[106:109], v[148:151], v[180:183], v[106:109]
	v_mfma_f32_16x16x32_bf16 v[94:97], v[140:143], v[188:191], v[94:97]
	v_mfma_f32_16x16x32_bf16 v[90:93], v[148:151], v[188:191], v[90:93]
	v_mfma_f32_16x16x32_bf16 v[78:81], v[140:143], v[206:209], v[78:81]
	v_mfma_f32_16x16x32_bf16 v[74:77], v[148:151], v[206:209], v[74:77]
	v_mfma_f32_16x16x32_bf16 v[126:129], v[144:147], v[176:179], v[126:129]
	v_mfma_f32_16x16x32_bf16 v[122:125], v[152:155], v[176:179], v[122:125]
	v_mfma_f32_16x16x32_bf16 v[110:113], v[144:147], v[184:187], v[110:113]
	v_mfma_f32_16x16x32_bf16 v[106:109], v[152:155], v[184:187], v[106:109]
	v_mfma_f32_16x16x32_bf16 v[94:97], v[144:147], v[202:205], v[94:97]
	v_mfma_f32_16x16x32_bf16 v[90:93], v[152:155], v[202:205], v[90:93]
	v_mfma_f32_16x16x32_bf16 v[78:81], v[144:147], v[210:213], v[78:81]
	v_mfma_f32_16x16x32_bf16 v[74:77], v[152:155], v[210:213], v[74:77]
	v_mfma_f32_16x16x32_bf16 v[118:121], v[156:159], v[172:175], v[118:121]
	v_mfma_f32_16x16x32_bf16 v[114:117], v[164:167], v[172:175], v[114:117]
	v_mfma_f32_16x16x32_bf16 v[102:105], v[156:159], v[180:183], v[102:105]
	v_mfma_f32_16x16x32_bf16 v[98:101], v[164:167], v[180:183], v[98:101]
	v_mfma_f32_16x16x32_bf16 v[86:89], v[156:159], v[188:191], v[86:89]
	v_mfma_f32_16x16x32_bf16 v[82:85], v[164:167], v[188:191], v[82:85]
	v_mfma_f32_16x16x32_bf16 v[70:73], v[156:159], v[206:209], v[70:73]
	v_mfma_f32_16x16x32_bf16 v[66:69], v[164:167], v[206:209], v[66:69]
	v_mfma_f32_16x16x32_bf16 v[118:121], v[160:163], v[176:179], v[118:121]
	v_mfma_f32_16x16x32_bf16 v[114:117], v[168:171], v[176:179], v[114:117]
	v_mfma_f32_16x16x32_bf16 v[102:105], v[160:163], v[184:187], v[102:105]
	v_mfma_f32_16x16x32_bf16 v[98:101], v[168:171], v[184:187], v[98:101]
	v_mfma_f32_16x16x32_bf16 v[86:89], v[160:163], v[202:205], v[86:89]
	v_mfma_f32_16x16x32_bf16 v[82:85], v[168:171], v[202:205], v[82:85]
	v_mfma_f32_16x16x32_bf16 v[70:73], v[160:163], v[210:213], v[70:73]
	v_mfma_f32_16x16x32_bf16 v[66:69], v[168:171], v[210:213], v[66:69]
	s_barrier
	s_add_i32 s30, s47, s3
	v_lshl_add_u64 v[192:193], v[192:193], 0, s[8:9]
	s_mov_b32 m0, s30
	ds_read_b128 v[172:175], v199 offset:49152
	ds_read_b128 v[176:179], v199 offset:50176
	ds_read_b128 v[180:183], v199 offset:51200
	ds_read_b128 v[184:187], v199 offset:52224
	ds_read_b128 v[188:191], v199 offset:53248
	ds_read_b128 v[202:205], v199 offset:54272
	ds_read_b128 v[206:209], v199 offset:55296
	ds_read_b128 v[210:213], v199 offset:56320
	global_load_lds_dwordx4 v[192:193], off
	s_add_i32 m0, s30, 0x2000
	s_add_u32 s28, s28, 0x80080
	v_lshl_add_u64 v[192:193], v[214:215], 0, s[8:9]
	s_addc_u32 s29, s29, 0
	s_add_i32 s30, s48, s3
	global_load_lds_dwordx4 v[192:193], off
	v_lshl_add_u64 v[192:193], s[28:29], 0, v[130:131]
	s_mov_b32 m0, s30
	s_nop 0
	global_load_lds_dwordx4 v[192:193], off
	v_lshl_add_u64 v[192:193], s[28:29], 0, v[132:133]
	s_add_i32 m0, s30, 0x2000
	s_nop 0
	global_load_lds_dwordx4 v[192:193], off
	v_lshl_add_u64 v[192:193], v[216:217], 0, s[8:9]
	s_mov_b32 m0, s38
	s_nop 0
	global_load_lds_dwordx4 v[192:193], off
	v_lshl_add_u64 v[192:193], v[218:219], 0, s[8:9]
	s_mov_b32 m0, s39
	s_nop 0
	global_load_lds_dwordx4 v[192:193], off
	s_waitcnt vmcnt(8)
	s_waitcnt lgkmcnt(0)
	s_barrier
	v_mfma_f32_16x16x32_bf16 v[62:65], v[140:143], v[172:175], v[62:65]
	v_mfma_f32_16x16x32_bf16 v[58:61], v[148:151], v[172:175], v[58:61]
	v_mfma_f32_16x16x32_bf16 v[46:49], v[140:143], v[180:183], v[46:49]
	v_mfma_f32_16x16x32_bf16 v[42:45], v[148:151], v[180:183], v[42:45]
	v_mfma_f32_16x16x32_bf16 v[30:33], v[140:143], v[188:191], v[30:33]
	v_mfma_f32_16x16x32_bf16 v[26:29], v[148:151], v[188:191], v[26:29]
	v_mfma_f32_16x16x32_bf16 v[14:17], v[140:143], v[206:209], v[14:17]
	v_mfma_f32_16x16x32_bf16 v[10:13], v[148:151], v[206:209], v[10:13]
	v_mfma_f32_16x16x32_bf16 v[62:65], v[144:147], v[176:179], v[62:65]
	v_mfma_f32_16x16x32_bf16 v[58:61], v[152:155], v[176:179], v[58:61]
	v_mfma_f32_16x16x32_bf16 v[46:49], v[144:147], v[184:187], v[46:49]
	v_mfma_f32_16x16x32_bf16 v[42:45], v[152:155], v[184:187], v[42:45]
	v_mfma_f32_16x16x32_bf16 v[30:33], v[144:147], v[202:205], v[30:33]
	v_mfma_f32_16x16x32_bf16 v[26:29], v[152:155], v[202:205], v[26:29]
	v_mfma_f32_16x16x32_bf16 v[14:17], v[144:147], v[210:213], v[14:17]
	v_mfma_f32_16x16x32_bf16 v[10:13], v[152:155], v[210:213], v[10:13]
	v_mfma_f32_16x16x32_bf16 v[54:57], v[156:159], v[172:175], v[54:57]
	v_mfma_f32_16x16x32_bf16 v[50:53], v[164:167], v[172:175], v[50:53]
	v_mfma_f32_16x16x32_bf16 v[38:41], v[156:159], v[180:183], v[38:41]
	v_mfma_f32_16x16x32_bf16 v[34:37], v[164:167], v[180:183], v[34:37]
	v_mfma_f32_16x16x32_bf16 v[22:25], v[156:159], v[188:191], v[22:25]
	v_mfma_f32_16x16x32_bf16 v[18:21], v[164:167], v[188:191], v[18:21]
	v_mfma_f32_16x16x32_bf16 v[6:9], v[156:159], v[206:209], v[6:9]
	v_mfma_f32_16x16x32_bf16 v[2:5], v[164:167], v[206:209], v[2:5]
	v_mfma_f32_16x16x32_bf16 v[54:57], v[160:163], v[176:179], v[54:57]
	v_mfma_f32_16x16x32_bf16 v[50:53], v[168:171], v[176:179], v[50:53]
	v_mfma_f32_16x16x32_bf16 v[38:41], v[160:163], v[184:187], v[38:41]
	v_mfma_f32_16x16x32_bf16 v[34:37], v[168:171], v[184:187], v[34:37]
	v_mfma_f32_16x16x32_bf16 v[22:25], v[160:163], v[202:205], v[22:25]
	v_mfma_f32_16x16x32_bf16 v[18:21], v[168:171], v[202:205], v[18:21]
	v_mfma_f32_16x16x32_bf16 v[6:9], v[160:163], v[210:213], v[6:9]
	v_mfma_f32_16x16x32_bf16 v[2:5], v[168:171], v[210:213], v[2:5]
	s_barrier
	s_add_i32 s46, s46, 2
	s_add_u32 s44, s44, 0x100
	s_addc_u32 s45, s45, 0
	s_add_u32 s26, s26, 0x100
	s_addc_u32 s27, s27, 0
	s_cmp_gt_u32 s46, 29
	s_cbranch_scc0 .LBB0_651
	s_and_b64 vcc, exec, s[10:11]
	s_cbranch_vccz .LBB0_654
	s_barrier

.LBB0_808:
	ds_read_b128 v[144:147], v152
	ds_read_b128 v[156:159], v152 offset:1024
	ds_read_b128 v[160:163], v152 offset:2048
	ds_read_b128 v[164:167], v152 offset:3072
	ds_read_b128 v[168:171], v153
	ds_read_b128 v[172:175], v153 offset:1024
	ds_read_b128 v[176:179], v153 offset:2048
	ds_read_b128 v[180:183], v153 offset:3072
	s_add_u32 s34, s30, 0xfff80080
	s_addc_u32 s35, s31, -1
	s_cmp_eq_u32 s55, 28
	s_cselect_b32 s37, s19, s35
	s_cselect_b32 s36, s51, s34
	s_cselect_b32 s35, s17, s54
	s_cselect_b32 s34, s52, s53
	v_lshl_add_u64 v[148:149], s[30:31], 0, v[138:139]
	s_add_i32 m0, s27, 0xc000
	ds_read_b128 v[184:187], v154
	ds_read_b128 v[188:191], v154 offset:1024
	ds_read_b128 v[196:199], v154 offset:2048
	ds_read_b128 v[200:203], v154 offset:3072
	ds_read_b128 v[204:207], v154 offset:4096
	ds_read_b128 v[208:211], v154 offset:5120
	ds_read_b128 v[212:215], v154 offset:6144
	ds_read_b128 v[216:219], v154 offset:7168
	global_load_lds_dwordx4 v[148:149], off
	v_lshl_add_u64 v[148:149], s[30:31], 0, v[140:141]
	s_add_i32 m0, s27, 0xe000
	s_nop 0
	global_load_lds_dwordx4 v[148:149], off
	s_waitcnt vmcnt(8)
	s_waitcnt lgkmcnt(0)
	s_barrier
	v_mfma_f32_16x16x32_bf16 v[126:129], v[144:147], v[184:187], v[126:129]
	v_mfma_f32_16x16x32_bf16 v[122:125], v[160:163], v[184:187], v[122:125]
	v_mfma_f32_16x16x32_bf16 v[110:113], v[144:147], v[196:199], v[110:113]
	v_mfma_f32_16x16x32_bf16 v[106:109], v[160:163], v[196:199], v[106:109]
	v_mfma_f32_16x16x32_bf16 v[94:97], v[144:147], v[204:207], v[94:97]
	v_mfma_f32_16x16x32_bf16 v[90:93], v[160:163], v[204:207], v[90:93]
	v_mfma_f32_16x16x32_bf16 v[78:81], v[144:147], v[212:215], v[78:81]
	v_mfma_f32_16x16x32_bf16 v[74:77], v[160:163], v[212:215], v[74:77]
	v_mfma_f32_16x16x32_bf16 v[126:129], v[156:159], v[188:191], v[126:129]
	v_mfma_f32_16x16x32_bf16 v[122:125], v[164:167], v[188:191], v[122:125]
	v_mfma_f32_16x16x32_bf16 v[110:113], v[156:159], v[200:203], v[110:113]
	v_mfma_f32_16x16x32_bf16 v[106:109], v[164:167], v[200:203], v[106:109]
	v_mfma_f32_16x16x32_bf16 v[94:97], v[156:159], v[208:211], v[94:97]
	v_mfma_f32_16x16x32_bf16 v[90:93], v[164:167], v[208:211], v[90:93]
	v_mfma_f32_16x16x32_bf16 v[78:81], v[156:159], v[216:219], v[78:81]
	v_mfma_f32_16x16x32_bf16 v[74:77], v[164:167], v[216:219], v[74:77]
	v_mfma_f32_16x16x32_bf16 v[118:121], v[168:171], v[184:187], v[118:121]
	v_mfma_f32_16x16x32_bf16 v[114:117], v[176:179], v[184:187], v[114:117]
	v_mfma_f32_16x16x32_bf16 v[102:105], v[168:171], v[196:199], v[102:105]
	v_mfma_f32_16x16x32_bf16 v[98:101], v[176:179], v[196:199], v[98:101]
	v_mfma_f32_16x16x32_bf16 v[86:89], v[168:171], v[204:207], v[86:89]
	v_mfma_f32_16x16x32_bf16 v[82:85], v[176:179], v[204:207], v[82:85]
	v_mfma_f32_16x16x32_bf16 v[70:73], v[168:171], v[212:215], v[70:73]
	v_mfma_f32_16x16x32_bf16 v[66:69], v[176:179], v[212:215], v[66:69]
	v_mfma_f32_16x16x32_bf16 v[118:121], v[172:175], v[188:191], v[118:121]
	v_mfma_f32_16x16x32_bf16 v[114:117], v[180:183], v[188:191], v[114:117]
	v_mfma_f32_16x16x32_bf16 v[102:105], v[172:175], v[200:203], v[102:105]
	v_mfma_f32_16x16x32_bf16 v[98:101], v[180:183], v[200:203], v[98:101]
	v_mfma_f32_16x16x32_bf16 v[86:89], v[172:175], v[208:211], v[86:89]
	v_mfma_f32_16x16x32_bf16 v[82:85], v[180:183], v[208:211], v[82:85]
	v_mfma_f32_16x16x32_bf16 v[70:73], v[172:175], v[216:219], v[70:73]
	v_mfma_f32_16x16x32_bf16 v[66:69], v[180:183], v[216:219], v[66:69]
	s_barrier
	s_add_i32 s56, s47, s38
	v_lshl_add_u64 v[148:149], s[34:35], 0, v[132:133]
	s_mov_b32 m0, s56
	ds_read_b128 v[184:187], v154 offset:16384
	ds_read_b128 v[188:191], v154 offset:17408
	ds_read_b128 v[196:199], v154 offset:18432
	ds_read_b128 v[200:203], v154 offset:19456
	ds_read_b128 v[204:207], v154 offset:20480
	ds_read_b128 v[208:211], v154 offset:21504
	ds_read_b128 v[212:215], v154 offset:22528
	ds_read_b128 v[216:219], v154 offset:23552
	global_load_lds_dwordx4 v[148:149], off
	s_add_i32 m0, s56, 0x2000
	s_add_u32 s56, s34, 0x80000
	v_lshl_add_u64 v[192:193], s[34:35], 0, v[136:137]
	s_addc_u32 s57, s35, 0
	s_add_i32 s58, s48, s38
	global_load_lds_dwordx4 v[192:193], off
	v_lshl_add_u64 v[220:221], s[56:57], 0, v[132:133]
	s_mov_b32 m0, s58
	v_lshl_add_u64 v[222:223], s[36:37], 0, v[134:135]
	global_load_lds_dwordx4 v[220:221], off
	v_lshl_add_u64 v[220:221], s[56:57], 0, v[136:137]
	s_add_i32 m0, s58, 0x2000
	s_nop 0
	global_load_lds_dwordx4 v[220:221], off
	v_lshl_add_u64 v[220:221], s[36:37], 0, v[130:131]
	s_mov_b32 m0, s27
	s_nop 0
	global_load_lds_dwordx4 v[220:221], off
	s_mov_b32 m0, s29
	s_nop 0
	global_load_lds_dwordx4 v[222:223], off
	s_waitcnt vmcnt(8)
	s_waitcnt lgkmcnt(0)
	s_barrier
	v_mfma_f32_16x16x32_bf16 v[62:65], v[144:147], v[184:187], v[62:65]
	v_mfma_f32_16x16x32_bf16 v[58:61], v[160:163], v[184:187], v[58:61]
	v_mfma_f32_16x16x32_bf16 v[46:49], v[144:147], v[196:199], v[46:49]
	v_mfma_f32_16x16x32_bf16 v[42:45], v[160:163], v[196:199], v[42:45]
	v_mfma_f32_16x16x32_bf16 v[30:33], v[144:147], v[204:207], v[30:33]
	v_mfma_f32_16x16x32_bf16 v[26:29], v[160:163], v[204:207], v[26:29]
	v_mfma_f32_16x16x32_bf16 v[14:17], v[144:147], v[212:215], v[14:17]
	v_mfma_f32_16x16x32_bf16 v[10:13], v[160:163], v[212:215], v[10:13]
	v_mfma_f32_16x16x32_bf16 v[62:65], v[156:159], v[188:191], v[62:65]
	v_mfma_f32_16x16x32_bf16 v[58:61], v[164:167], v[188:191], v[58:61]
	v_mfma_f32_16x16x32_bf16 v[46:49], v[156:159], v[200:203], v[46:49]
	v_mfma_f32_16x16x32_bf16 v[42:45], v[164:167], v[200:203], v[42:45]
	v_mfma_f32_16x16x32_bf16 v[30:33], v[156:159], v[208:211], v[30:33]
	v_mfma_f32_16x16x32_bf16 v[26:29], v[164:167], v[208:211], v[26:29]
	v_mfma_f32_16x16x32_bf16 v[14:17], v[156:159], v[216:219], v[14:17]
	v_mfma_f32_16x16x32_bf16 v[10:13], v[164:167], v[216:219], v[10:13]
	v_mfma_f32_16x16x32_bf16 v[54:57], v[168:171], v[184:187], v[54:57]
	v_mfma_f32_16x16x32_bf16 v[50:53], v[176:179], v[184:187], v[50:53]
	v_mfma_f32_16x16x32_bf16 v[38:41], v[168:171], v[196:199], v[38:41]
	v_mfma_f32_16x16x32_bf16 v[34:37], v[176:179], v[196:199], v[34:37]
	v_mfma_f32_16x16x32_bf16 v[22:25], v[168:171], v[204:207], v[22:25]
	v_mfma_f32_16x16x32_bf16 v[18:21], v[176:179], v[204:207], v[18:21]
	v_mfma_f32_16x16x32_bf16 v[6:9], v[168:171], v[212:215], v[6:9]
	v_mfma_f32_16x16x32_bf16 v[2:5], v[176:179], v[212:215], v[2:5]
	v_mfma_f32_16x16x32_bf16 v[54:57], v[172:175], v[188:191], v[54:57]
	v_mfma_f32_16x16x32_bf16 v[50:53], v[180:183], v[188:191], v[50:53]
	v_mfma_f32_16x16x32_bf16 v[38:41], v[172:175], v[200:203], v[38:41]
	v_mfma_f32_16x16x32_bf16 v[34:37], v[180:183], v[200:203], v[34:37]
	v_mfma_f32_16x16x32_bf16 v[22:25], v[172:175], v[208:211], v[22:25]
	v_mfma_f32_16x16x32_bf16 v[18:21], v[180:183], v[208:211], v[18:21]
	v_mfma_f32_16x16x32_bf16 v[6:9], v[172:175], v[216:219], v[6:9]
	v_mfma_f32_16x16x32_bf16 v[2:5], v[180:183], v[216:219], v[2:5]
	s_barrier
	s_add_i32 s56, 0, 0x18000
	v_add_u32_e32 v155, s56, v150
	s_add_i32 s57, 0, 0x1c000
	ds_read_b128 v[144:147], v155
	ds_read_b128 v[156:159], v155 offset:1024
	ds_read_b128 v[160:163], v155 offset:2048
	ds_read_b128 v[164:167], v155 offset:3072
	v_add_u32_e32 v155, s57, v150
	ds_read_b128 v[168:171], v155
	ds_read_b128 v[172:175], v155 offset:1024
	ds_read_b128 v[176:179], v155 offset:2048
	ds_read_b128 v[180:183], v155 offset:3072
	s_add_u32 s36, s36, 0x80000
	s_addc_u32 s37, s37, 0
	s_mov_b32 m0, s39
	v_lshl_add_u64 v[224:225], s[36:37], 0, v[130:131]
	ds_read_b128 v[184:187], v154 offset:32768
	ds_read_b128 v[188:191], v154 offset:33792
	ds_read_b128 v[196:199], v154 offset:34816
	ds_read_b128 v[200:203], v154 offset:35840
	ds_read_b128 v[204:207], v154 offset:36864
	ds_read_b128 v[208:211], v154 offset:37888
	ds_read_b128 v[212:215], v154 offset:38912
	ds_read_b128 v[216:219], v154 offset:39936
	global_load_lds_dwordx4 v[224:225], off
	v_lshl_add_u64 v[224:225], s[36:37], 0, v[134:135]
	s_mov_b32 m0, s40
	s_nop 0
	global_load_lds_dwordx4 v[224:225], off
	s_waitcnt vmcnt(8)
	s_waitcnt lgkmcnt(0)
	s_barrier
	v_mfma_f32_16x16x32_bf16 v[126:129], v[144:147], v[184:187], v[126:129]
	v_mfma_f32_16x16x32_bf16 v[122:125], v[160:163], v[184:187], v[122:125]
	v_mfma_f32_16x16x32_bf16 v[110:113], v[144:147], v[196:199], v[110:113]
	v_mfma_f32_16x16x32_bf16 v[106:109], v[160:163], v[196:199], v[106:109]
	v_mfma_f32_16x16x32_bf16 v[94:97], v[144:147], v[204:207], v[94:97]
	v_mfma_f32_16x16x32_bf16 v[90:93], v[160:163], v[204:207], v[90:93]
	v_mfma_f32_16x16x32_bf16 v[78:81], v[144:147], v[212:215], v[78:81]
	v_mfma_f32_16x16x32_bf16 v[74:77], v[160:163], v[212:215], v[74:77]
	v_mfma_f32_16x16x32_bf16 v[126:129], v[156:159], v[188:191], v[126:129]
	v_mfma_f32_16x16x32_bf16 v[122:125], v[164:167], v[188:191], v[122:125]
	v_mfma_f32_16x16x32_bf16 v[110:113], v[156:159], v[200:203], v[110:113]
	v_mfma_f32_16x16x32_bf16 v[106:109], v[164:167], v[200:203], v[106:109]
	v_mfma_f32_16x16x32_bf16 v[94:97], v[156:159], v[208:211], v[94:97]
	v_mfma_f32_16x16x32_bf16 v[90:93], v[164:167], v[208:211], v[90:93]
	v_mfma_f32_16x16x32_bf16 v[78:81], v[156:159], v[216:219], v[78:81]
	v_mfma_f32_16x16x32_bf16 v[74:77], v[164:167], v[216:219], v[74:77]
	v_mfma_f32_16x16x32_bf16 v[118:121], v[168:171], v[184:187], v[118:121]
	v_mfma_f32_16x16x32_bf16 v[114:117], v[176:179], v[184:187], v[114:117]
	v_mfma_f32_16x16x32_bf16 v[102:105], v[168:171], v[196:199], v[102:105]
	v_mfma_f32_16x16x32_bf16 v[98:101], v[176:179], v[196:199], v[98:101]
	v_mfma_f32_16x16x32_bf16 v[86:89], v[168:171], v[204:207], v[86:89]
	v_mfma_f32_16x16x32_bf16 v[82:85], v[176:179], v[204:207], v[82:85]
	v_mfma_f32_16x16x32_bf16 v[70:73], v[168:171], v[212:215], v[70:73]
	v_mfma_f32_16x16x32_bf16 v[66:69], v[176:179], v[212:215], v[66:69]
	v_mfma_f32_16x16x32_bf16 v[118:121], v[172:175], v[188:191], v[118:121]
	v_mfma_f32_16x16x32_bf16 v[114:117], v[180:183], v[188:191], v[114:117]
	v_mfma_f32_16x16x32_bf16 v[102:105], v[172:175], v[200:203], v[102:105]
	v_mfma_f32_16x16x32_bf16 v[98:101], v[180:183], v[200:203], v[98:101]
	v_mfma_f32_16x16x32_bf16 v[86:89], v[172:175], v[208:211], v[86:89]
	v_mfma_f32_16x16x32_bf16 v[82:85], v[180:183], v[208:211], v[82:85]
	v_mfma_f32_16x16x32_bf16 v[70:73], v[172:175], v[216:219], v[70:73]
	v_mfma_f32_16x16x32_bf16 v[66:69], v[180:183], v[216:219], v[66:69]
	s_barrier
	s_add_i32 s36, s56, s38
	v_lshl_add_u64 v[148:149], v[148:149], 0, s[10:11]
	s_mov_b32 m0, s36
	ds_read_b128 v[184:187], v154 offset:49152
	ds_read_b128 v[188:191], v154 offset:50176
	ds_read_b128 v[196:199], v154 offset:51200
	ds_read_b128 v[200:203], v154 offset:52224
	ds_read_b128 v[204:207], v154 offset:53248
	ds_read_b128 v[208:211], v154 offset:54272
	ds_read_b128 v[212:215], v154 offset:55296
	ds_read_b128 v[216:219], v154 offset:56320
	global_load_lds_dwordx4 v[148:149], off
	s_add_i32 m0, s36, 0x2000
	s_add_u32 s34, s34, 0x80080
	v_lshl_add_u64 v[148:149], v[192:193], 0, s[10:11]
	s_addc_u32 s35, s35, 0
	s_add_i32 s36, s57, s38
	global_load_lds_dwordx4 v[148:149], off
	v_lshl_add_u64 v[148:149], s[34:35], 0, v[132:133]
	s_mov_b32 m0, s36
	s_nop 0
	global_load_lds_dwordx4 v[148:149], off
	v_lshl_add_u64 v[148:149], s[34:35], 0, v[136:137]
	s_add_i32 m0, s36, 0x2000
	s_nop 0
	global_load_lds_dwordx4 v[148:149], off
	v_lshl_add_u64 v[148:149], v[220:221], 0, s[10:11]
	s_mov_b32 m0, s42
	s_nop 0
	global_load_lds_dwordx4 v[148:149], off
	v_lshl_add_u64 v[148:149], v[222:223], 0, s[10:11]
	s_mov_b32 m0, s43
	s_nop 0
	global_load_lds_dwordx4 v[148:149], off
	s_waitcnt vmcnt(8)
	s_waitcnt lgkmcnt(0)
	s_barrier
	v_mfma_f32_16x16x32_bf16 v[62:65], v[144:147], v[184:187], v[62:65]
	v_mfma_f32_16x16x32_bf16 v[58:61], v[160:163], v[184:187], v[58:61]
	v_mfma_f32_16x16x32_bf16 v[46:49], v[144:147], v[196:199], v[46:49]
	v_mfma_f32_16x16x32_bf16 v[42:45], v[160:163], v[196:199], v[42:45]
	v_mfma_f32_16x16x32_bf16 v[30:33], v[144:147], v[204:207], v[30:33]
	v_mfma_f32_16x16x32_bf16 v[26:29], v[160:163], v[204:207], v[26:29]
	v_mfma_f32_16x16x32_bf16 v[14:17], v[144:147], v[212:215], v[14:17]
	v_mfma_f32_16x16x32_bf16 v[10:13], v[160:163], v[212:215], v[10:13]
	v_mfma_f32_16x16x32_bf16 v[62:65], v[156:159], v[188:191], v[62:65]
	v_mfma_f32_16x16x32_bf16 v[58:61], v[164:167], v[188:191], v[58:61]
	v_mfma_f32_16x16x32_bf16 v[46:49], v[156:159], v[200:203], v[46:49]
	v_mfma_f32_16x16x32_bf16 v[42:45], v[164:167], v[200:203], v[42:45]
	v_mfma_f32_16x16x32_bf16 v[30:33], v[156:159], v[208:211], v[30:33]
	v_mfma_f32_16x16x32_bf16 v[26:29], v[164:167], v[208:211], v[26:29]
	v_mfma_f32_16x16x32_bf16 v[14:17], v[156:159], v[216:219], v[14:17]
	v_mfma_f32_16x16x32_bf16 v[10:13], v[164:167], v[216:219], v[10:13]
	v_mfma_f32_16x16x32_bf16 v[54:57], v[168:171], v[184:187], v[54:57]
	v_mfma_f32_16x16x32_bf16 v[50:53], v[176:179], v[184:187], v[50:53]
	v_mfma_f32_16x16x32_bf16 v[38:41], v[168:171], v[196:199], v[38:41]
	v_mfma_f32_16x16x32_bf16 v[34:37], v[176:179], v[196:199], v[34:37]
	v_mfma_f32_16x16x32_bf16 v[22:25], v[168:171], v[204:207], v[22:25]
	v_mfma_f32_16x16x32_bf16 v[18:21], v[176:179], v[204:207], v[18:21]
	v_mfma_f32_16x16x32_bf16 v[6:9], v[168:171], v[212:215], v[6:9]
	v_mfma_f32_16x16x32_bf16 v[2:5], v[176:179], v[212:215], v[2:5]
	v_mfma_f32_16x16x32_bf16 v[54:57], v[172:175], v[188:191], v[54:57]
	v_mfma_f32_16x16x32_bf16 v[50:53], v[180:183], v[188:191], v[50:53]
	v_mfma_f32_16x16x32_bf16 v[38:41], v[172:175], v[200:203], v[38:41]
	v_mfma_f32_16x16x32_bf16 v[34:37], v[180:183], v[200:203], v[34:37]
	v_mfma_f32_16x16x32_bf16 v[22:25], v[172:175], v[208:211], v[22:25]
	v_mfma_f32_16x16x32_bf16 v[18:21], v[180:183], v[208:211], v[18:21]
	v_mfma_f32_16x16x32_bf16 v[6:9], v[172:175], v[216:219], v[6:9]
	v_mfma_f32_16x16x32_bf16 v[2:5], v[180:183], v[216:219], v[2:5]
	s_barrier
	s_add_i32 s55, s55, 2
	s_add_u32 s53, s53, 0x100
	s_addc_u32 s54, s54, 0
	s_add_u32 s30, s30, 0x100
	s_addc_u32 s31, s31, 0
	s_cmp_gt_u32 s55, 29
	s_cbranch_scc0 .LBB0_808
	s_and_b64 vcc, exec, s[12:13]
	s_cbranch_vccz .LBB0_811
	s_barrier

.LBB0_1031:
	ds_read_b128 v[144:147], v139
	ds_read_b128 v[148:151], v139 offset:1024
	ds_read_b128 v[152:155], v139 offset:2048
	ds_read_b128 v[156:159], v139 offset:3072
	ds_read_b128 v[164:167], v140
	ds_read_b128 v[168:171], v140 offset:1024
	ds_read_b128 v[172:175], v140 offset:2048
	ds_read_b128 v[176:179], v140 offset:3072
	s_add_u32 s12, s8, s10
	s_addc_u32 s13, s9, s11
	s_add_u32 s12, s12, 0x2000100
	s_addc_u32 s13, s13, 0
	s_add_u32 s42, s27, s10
	s_addc_u32 s43, s28, s11
	s_cmpk_eq_i32 s10, 0x3f00
	s_cselect_b32 s15, s3, s13
	s_cselect_b32 s14, s2, s12
	s_cselect_b32 s13, s1, s43
	s_cselect_b32 s12, s0, s42
	s_mov_b32 m0, s30
	v_lshl_add_u64 v[160:161], v[134:135], 0, s[10:11]
	ds_read_b128 v[180:183], v141
	ds_read_b128 v[184:187], v141 offset:1024
	ds_read_b128 v[188:191], v141 offset:2048
	ds_read_b128 v[196:199], v141 offset:3072
	ds_read_b128 v[200:203], v141 offset:4096
	ds_read_b128 v[204:207], v141 offset:5120
	ds_read_b128 v[208:211], v141 offset:6144
	ds_read_b128 v[212:215], v141 offset:7168
	global_load_lds_dwordx4 v[160:161], off
	v_lshl_add_u64 v[160:161], v[136:137], 0, s[10:11]
	s_mov_b32 m0, s31
	s_nop 0
	global_load_lds_dwordx4 v[160:161], off
	s_waitcnt vmcnt(8)
	s_waitcnt lgkmcnt(0)
	s_barrier
	v_mfma_f32_16x16x32_bf16 v[126:129], v[144:147], v[180:183], v[126:129]
	v_mfma_f32_16x16x32_bf16 v[122:125], v[152:155], v[180:183], v[122:125]
	v_mfma_f32_16x16x32_bf16 v[110:113], v[144:147], v[188:191], v[110:113]
	v_mfma_f32_16x16x32_bf16 v[106:109], v[152:155], v[188:191], v[106:109]
	v_mfma_f32_16x16x32_bf16 v[94:97], v[144:147], v[200:203], v[94:97]
	v_mfma_f32_16x16x32_bf16 v[90:93], v[152:155], v[200:203], v[90:93]
	v_mfma_f32_16x16x32_bf16 v[78:81], v[144:147], v[208:211], v[78:81]
	v_mfma_f32_16x16x32_bf16 v[74:77], v[152:155], v[208:211], v[74:77]
	v_mfma_f32_16x16x32_bf16 v[126:129], v[148:151], v[184:187], v[126:129]
	v_mfma_f32_16x16x32_bf16 v[122:125], v[156:159], v[184:187], v[122:125]
	v_mfma_f32_16x16x32_bf16 v[110:113], v[148:151], v[196:199], v[110:113]
	v_mfma_f32_16x16x32_bf16 v[106:109], v[156:159], v[196:199], v[106:109]
	v_mfma_f32_16x16x32_bf16 v[94:97], v[148:151], v[204:207], v[94:97]
	v_mfma_f32_16x16x32_bf16 v[90:93], v[156:159], v[204:207], v[90:93]
	v_mfma_f32_16x16x32_bf16 v[78:81], v[148:151], v[212:215], v[78:81]
	v_mfma_f32_16x16x32_bf16 v[74:77], v[156:159], v[212:215], v[74:77]
	v_mfma_f32_16x16x32_bf16 v[118:121], v[164:167], v[180:183], v[118:121]
	v_mfma_f32_16x16x32_bf16 v[114:117], v[172:175], v[180:183], v[114:117]
	v_mfma_f32_16x16x32_bf16 v[102:105], v[164:167], v[188:191], v[102:105]
	v_mfma_f32_16x16x32_bf16 v[98:101], v[172:175], v[188:191], v[98:101]
	v_mfma_f32_16x16x32_bf16 v[86:89], v[164:167], v[200:203], v[86:89]
	v_mfma_f32_16x16x32_bf16 v[82:85], v[172:175], v[200:203], v[82:85]
	v_mfma_f32_16x16x32_bf16 v[70:73], v[164:167], v[208:211], v[70:73]
	v_mfma_f32_16x16x32_bf16 v[66:69], v[172:175], v[208:211], v[66:69]
	v_mfma_f32_16x16x32_bf16 v[118:121], v[168:171], v[184:187], v[118:121]
	v_mfma_f32_16x16x32_bf16 v[114:117], v[176:179], v[184:187], v[114:117]
	v_mfma_f32_16x16x32_bf16 v[102:105], v[168:171], v[196:199], v[102:105]
	v_mfma_f32_16x16x32_bf16 v[98:101], v[176:179], v[196:199], v[98:101]
	v_mfma_f32_16x16x32_bf16 v[86:89], v[168:171], v[204:207], v[86:89]
	v_mfma_f32_16x16x32_bf16 v[82:85], v[176:179], v[204:207], v[82:85]
	v_mfma_f32_16x16x32_bf16 v[70:73], v[168:171], v[212:215], v[70:73]
	v_mfma_f32_16x16x32_bf16 v[66:69], v[176:179], v[212:215], v[66:69]
	s_barrier
	s_mov_b32 m0, s34
	v_lshl_add_u64 v[160:161], s[12:13], 0, v[130:131]
	s_add_u32 s42, s12, 0x200000
	ds_read_b128 v[180:183], v141 offset:16384
	ds_read_b128 v[184:187], v141 offset:17408
	ds_read_b128 v[188:191], v141 offset:18432
	ds_read_b128 v[196:199], v141 offset:19456
	ds_read_b128 v[200:203], v141 offset:20480
	ds_read_b128 v[204:207], v141 offset:21504
	ds_read_b128 v[208:211], v141 offset:22528
	ds_read_b128 v[212:215], v141 offset:23552
	global_load_lds_dwordx4 v[160:161], off
	v_lshl_add_u64 v[192:193], s[12:13], 0, v[132:133]
	s_mov_b32 m0, s35
	s_addc_u32 s43, s13, 0
	global_load_lds_dwordx4 v[192:193], off
	v_lshl_add_u64 v[216:217], s[42:43], 0, v[130:131]
	s_mov_b32 m0, s36
	v_lshl_add_u64 v[218:219], s[14:15], 0, v[132:133]
	global_load_lds_dwordx4 v[216:217], off
	v_lshl_add_u64 v[216:217], s[42:43], 0, v[132:133]
	s_mov_b32 m0, s37
	s_nop 0
	global_load_lds_dwordx4 v[216:217], off
	v_lshl_add_u64 v[216:217], s[14:15], 0, v[130:131]
	s_mov_b32 m0, s20
	s_nop 0
	global_load_lds_dwordx4 v[216:217], off
	s_mov_b32 m0, s21
	s_nop 0
	global_load_lds_dwordx4 v[218:219], off
	s_waitcnt vmcnt(8)
	s_waitcnt lgkmcnt(0)
	s_barrier
	v_mfma_f32_16x16x32_bf16 v[62:65], v[144:147], v[180:183], v[62:65]
	v_mfma_f32_16x16x32_bf16 v[58:61], v[152:155], v[180:183], v[58:61]
	v_mfma_f32_16x16x32_bf16 v[46:49], v[144:147], v[188:191], v[46:49]
	v_mfma_f32_16x16x32_bf16 v[42:45], v[152:155], v[188:191], v[42:45]
	v_mfma_f32_16x16x32_bf16 v[30:33], v[144:147], v[200:203], v[30:33]
	v_mfma_f32_16x16x32_bf16 v[26:29], v[152:155], v[200:203], v[26:29]
	v_mfma_f32_16x16x32_bf16 v[14:17], v[144:147], v[208:211], v[14:17]
	v_mfma_f32_16x16x32_bf16 v[10:13], v[152:155], v[208:211], v[10:13]
	v_mfma_f32_16x16x32_bf16 v[62:65], v[148:151], v[184:187], v[62:65]
	v_mfma_f32_16x16x32_bf16 v[58:61], v[156:159], v[184:187], v[58:61]
	v_mfma_f32_16x16x32_bf16 v[46:49], v[148:151], v[196:199], v[46:49]
	v_mfma_f32_16x16x32_bf16 v[42:45], v[156:159], v[196:199], v[42:45]
	v_mfma_f32_16x16x32_bf16 v[30:33], v[148:151], v[204:207], v[30:33]
	v_mfma_f32_16x16x32_bf16 v[26:29], v[156:159], v[204:207], v[26:29]
	v_mfma_f32_16x16x32_bf16 v[14:17], v[148:151], v[212:215], v[14:17]
	v_mfma_f32_16x16x32_bf16 v[10:13], v[156:159], v[212:215], v[10:13]
	v_mfma_f32_16x16x32_bf16 v[54:57], v[164:167], v[180:183], v[54:57]
	v_mfma_f32_16x16x32_bf16 v[50:53], v[172:175], v[180:183], v[50:53]
	v_mfma_f32_16x16x32_bf16 v[38:41], v[164:167], v[188:191], v[38:41]
	v_mfma_f32_16x16x32_bf16 v[34:37], v[172:175], v[188:191], v[34:37]
	v_mfma_f32_16x16x32_bf16 v[22:25], v[164:167], v[200:203], v[22:25]
	v_mfma_f32_16x16x32_bf16 v[18:21], v[172:175], v[200:203], v[18:21]
	v_mfma_f32_16x16x32_bf16 v[6:9], v[164:167], v[208:211], v[6:9]
	v_mfma_f32_16x16x32_bf16 v[2:5], v[172:175], v[208:211], v[2:5]
	v_mfma_f32_16x16x32_bf16 v[54:57], v[168:171], v[184:187], v[54:57]
	v_mfma_f32_16x16x32_bf16 v[50:53], v[176:179], v[184:187], v[50:53]
	v_mfma_f32_16x16x32_bf16 v[38:41], v[168:171], v[196:199], v[38:41]
	v_mfma_f32_16x16x32_bf16 v[34:37], v[176:179], v[196:199], v[34:37]
	v_mfma_f32_16x16x32_bf16 v[22:25], v[168:171], v[204:207], v[22:25]
	v_mfma_f32_16x16x32_bf16 v[18:21], v[176:179], v[204:207], v[18:21]
	v_mfma_f32_16x16x32_bf16 v[6:9], v[168:171], v[212:215], v[6:9]
	v_mfma_f32_16x16x32_bf16 v[2:5], v[176:179], v[212:215], v[2:5]
	s_barrier
	ds_read_b128 v[144:147], v142
	ds_read_b128 v[148:151], v142 offset:1024
	ds_read_b128 v[152:155], v142 offset:2048
	ds_read_b128 v[156:159], v142 offset:3072
	ds_read_b128 v[164:167], v143
	ds_read_b128 v[168:171], v143 offset:1024
	ds_read_b128 v[172:175], v143 offset:2048
	ds_read_b128 v[176:179], v143 offset:3072
	s_add_u32 s14, s14, 0x200000
	s_addc_u32 s15, s15, 0
	s_mov_b32 m0, s22
	v_lshl_add_u64 v[220:221], s[14:15], 0, v[130:131]
	ds_read_b128 v[180:183], v141 offset:32768
	ds_read_b128 v[184:187], v141 offset:33792
	ds_read_b128 v[188:191], v141 offset:34816
	ds_read_b128 v[196:199], v141 offset:35840
	ds_read_b128 v[200:203], v141 offset:36864
	ds_read_b128 v[204:207], v141 offset:37888
	ds_read_b128 v[208:211], v141 offset:38912
	ds_read_b128 v[212:215], v141 offset:39936
	global_load_lds_dwordx4 v[220:221], off
	v_lshl_add_u64 v[220:221], s[14:15], 0, v[132:133]
	s_mov_b32 m0, s23
	s_nop 0
	global_load_lds_dwordx4 v[220:221], off
	s_waitcnt vmcnt(8)
	s_waitcnt lgkmcnt(0)
	s_barrier
	v_mfma_f32_16x16x32_bf16 v[126:129], v[144:147], v[180:183], v[126:129]
	v_mfma_f32_16x16x32_bf16 v[122:125], v[152:155], v[180:183], v[122:125]
	v_mfma_f32_16x16x32_bf16 v[110:113], v[144:147], v[188:191], v[110:113]
	v_mfma_f32_16x16x32_bf16 v[106:109], v[152:155], v[188:191], v[106:109]
	v_mfma_f32_16x16x32_bf16 v[94:97], v[144:147], v[200:203], v[94:97]
	v_mfma_f32_16x16x32_bf16 v[90:93], v[152:155], v[200:203], v[90:93]
	v_mfma_f32_16x16x32_bf16 v[78:81], v[144:147], v[208:211], v[78:81]
	v_mfma_f32_16x16x32_bf16 v[74:77], v[152:155], v[208:211], v[74:77]
	v_mfma_f32_16x16x32_bf16 v[126:129], v[148:151], v[184:187], v[126:129]
	v_mfma_f32_16x16x32_bf16 v[122:125], v[156:159], v[184:187], v[122:125]
	v_mfma_f32_16x16x32_bf16 v[110:113], v[148:151], v[196:199], v[110:113]
	v_mfma_f32_16x16x32_bf16 v[106:109], v[156:159], v[196:199], v[106:109]
	v_mfma_f32_16x16x32_bf16 v[94:97], v[148:151], v[204:207], v[94:97]
	v_mfma_f32_16x16x32_bf16 v[90:93], v[156:159], v[204:207], v[90:93]
	v_mfma_f32_16x16x32_bf16 v[78:81], v[148:151], v[212:215], v[78:81]
	v_mfma_f32_16x16x32_bf16 v[74:77], v[156:159], v[212:215], v[74:77]
	v_mfma_f32_16x16x32_bf16 v[118:121], v[164:167], v[180:183], v[118:121]
	v_mfma_f32_16x16x32_bf16 v[114:117], v[172:175], v[180:183], v[114:117]
	v_mfma_f32_16x16x32_bf16 v[102:105], v[164:167], v[188:191], v[102:105]
	v_mfma_f32_16x16x32_bf16 v[98:101], v[172:175], v[188:191], v[98:101]
	v_mfma_f32_16x16x32_bf16 v[86:89], v[164:167], v[200:203], v[86:89]
	v_mfma_f32_16x16x32_bf16 v[82:85], v[172:175], v[200:203], v[82:85]
	v_mfma_f32_16x16x32_bf16 v[70:73], v[164:167], v[208:211], v[70:73]
	v_mfma_f32_16x16x32_bf16 v[66:69], v[172:175], v[208:211], v[66:69]
	v_mfma_f32_16x16x32_bf16 v[118:121], v[168:171], v[184:187], v[118:121]
	v_mfma_f32_16x16x32_bf16 v[114:117], v[176:179], v[184:187], v[114:117]
	v_mfma_f32_16x16x32_bf16 v[102:105], v[168:171], v[196:199], v[102:105]
	v_mfma_f32_16x16x32_bf16 v[98:101], v[176:179], v[196:199], v[98:101]
	v_mfma_f32_16x16x32_bf16 v[86:89], v[168:171], v[204:207], v[86:89]
	v_mfma_f32_16x16x32_bf16 v[82:85], v[176:179], v[204:207], v[82:85]
	v_mfma_f32_16x16x32_bf16 v[70:73], v[168:171], v[212:215], v[70:73]
	v_mfma_f32_16x16x32_bf16 v[66:69], v[176:179], v[212:215], v[66:69]
	s_barrier
	s_mov_b32 m0, s38
	v_lshl_add_u64 v[160:161], v[160:161], 0, s[4:5]
	s_add_u32 s12, s12, 0x200080
	ds_read_b128 v[180:183], v141 offset:49152
	ds_read_b128 v[184:187], v141 offset:50176
	ds_read_b128 v[188:191], v141 offset:51200
	ds_read_b128 v[196:199], v141 offset:52224
	ds_read_b128 v[200:203], v141 offset:53248
	ds_read_b128 v[204:207], v141 offset:54272
	ds_read_b128 v[208:211], v141 offset:55296
	ds_read_b128 v[212:215], v141 offset:56320
	global_load_lds_dwordx4 v[160:161], off
	v_lshl_add_u64 v[160:161], v[192:193], 0, s[4:5]
	s_mov_b32 m0, s39
	s_addc_u32 s13, s13, 0
	global_load_lds_dwordx4 v[160:161], off
	v_lshl_add_u64 v[160:161], s[12:13], 0, v[130:131]
	s_mov_b32 m0, s40
	s_nop 0
	global_load_lds_dwordx4 v[160:161], off
	v_lshl_add_u64 v[160:161], s[12:13], 0, v[132:133]
	s_mov_b32 m0, s41
	s_nop 0
	global_load_lds_dwordx4 v[160:161], off
	v_lshl_add_u64 v[160:161], v[216:217], 0, s[4:5]
	s_mov_b32 m0, s25
	s_nop 0
	global_load_lds_dwordx4 v[160:161], off
	v_lshl_add_u64 v[160:161], v[218:219], 0, s[4:5]
	s_mov_b32 m0, s26
	s_nop 0
	global_load_lds_dwordx4 v[160:161], off
	s_waitcnt vmcnt(8)
	s_waitcnt lgkmcnt(0)
	s_barrier
	v_mfma_f32_16x16x32_bf16 v[62:65], v[144:147], v[180:183], v[62:65]
	v_mfma_f32_16x16x32_bf16 v[58:61], v[152:155], v[180:183], v[58:61]
	v_mfma_f32_16x16x32_bf16 v[46:49], v[144:147], v[188:191], v[46:49]
	v_mfma_f32_16x16x32_bf16 v[42:45], v[152:155], v[188:191], v[42:45]
	v_mfma_f32_16x16x32_bf16 v[30:33], v[144:147], v[200:203], v[30:33]
	v_mfma_f32_16x16x32_bf16 v[26:29], v[152:155], v[200:203], v[26:29]
	v_mfma_f32_16x16x32_bf16 v[14:17], v[144:147], v[208:211], v[14:17]
	v_mfma_f32_16x16x32_bf16 v[10:13], v[152:155], v[208:211], v[10:13]
	v_mfma_f32_16x16x32_bf16 v[62:65], v[148:151], v[184:187], v[62:65]
	v_mfma_f32_16x16x32_bf16 v[58:61], v[156:159], v[184:187], v[58:61]
	v_mfma_f32_16x16x32_bf16 v[46:49], v[148:151], v[196:199], v[46:49]
	v_mfma_f32_16x16x32_bf16 v[42:45], v[156:159], v[196:199], v[42:45]
	v_mfma_f32_16x16x32_bf16 v[30:33], v[148:151], v[204:207], v[30:33]
	v_mfma_f32_16x16x32_bf16 v[26:29], v[156:159], v[204:207], v[26:29]
	v_mfma_f32_16x16x32_bf16 v[14:17], v[148:151], v[212:215], v[14:17]
	v_mfma_f32_16x16x32_bf16 v[10:13], v[156:159], v[212:215], v[10:13]
	v_mfma_f32_16x16x32_bf16 v[54:57], v[164:167], v[180:183], v[54:57]
	v_mfma_f32_16x16x32_bf16 v[50:53], v[172:175], v[180:183], v[50:53]
	v_mfma_f32_16x16x32_bf16 v[38:41], v[164:167], v[188:191], v[38:41]
	v_mfma_f32_16x16x32_bf16 v[34:37], v[172:175], v[188:191], v[34:37]
	v_mfma_f32_16x16x32_bf16 v[22:25], v[164:167], v[200:203], v[22:25]
	v_mfma_f32_16x16x32_bf16 v[18:21], v[172:175], v[200:203], v[18:21]
	v_mfma_f32_16x16x32_bf16 v[6:9], v[164:167], v[208:211], v[6:9]
	v_mfma_f32_16x16x32_bf16 v[2:5], v[172:175], v[208:211], v[2:5]
	v_mfma_f32_16x16x32_bf16 v[54:57], v[168:171], v[184:187], v[54:57]
	v_mfma_f32_16x16x32_bf16 v[50:53], v[176:179], v[184:187], v[50:53]
	v_mfma_f32_16x16x32_bf16 v[38:41], v[168:171], v[196:199], v[38:41]
	v_mfma_f32_16x16x32_bf16 v[34:37], v[176:179], v[196:199], v[34:37]
	v_mfma_f32_16x16x32_bf16 v[22:25], v[168:171], v[204:207], v[22:25]
	v_mfma_f32_16x16x32_bf16 v[18:21], v[176:179], v[204:207], v[18:21]
	v_mfma_f32_16x16x32_bf16 v[6:9], v[168:171], v[212:215], v[6:9]
	v_mfma_f32_16x16x32_bf16 v[2:5], v[176:179], v[212:215], v[2:5]
	s_barrier
	s_add_i32 s29, s29, 2
	s_add_u32 s10, s10, 0x100
	s_addc_u32 s11, s11, 0
	s_cmpk_lt_u32 s29, 0x7e
	s_cbranch_scc1 .LBB0_1031
	s_waitcnt vmcnt(0)
	s_cmpk_gt_u32 s19, 0xff
	s_cbranch_scc1 .LBB0_1034
	s_barrier
